# v49 + sgu prompt u-value loads: 8 dwordx2 loads paired into 4 dwordx4 loads, per-lane layout restored with v_permlane16_swap after the wait
# baseline (speedup 1.0000x reference)
; #define LAS __attribute__((address_space(3)))
; __device__ __forceinline__ unsigned pk2(float lo, float hi) { unsigned r; asm("v_cvt_pk_bf16_f32 %0, %1, %2" : "=v"(r) : "v"(lo), "v"(hi)); return r; }
; __device__ __forceinline__ void sgu_prompt_item(int item, const u16* PROJ, u16* MIXIN, const float* gln, const float* bln, const float* wsp, const float* bsp, LAS unsigned char* lds, int& hh_cached) {
;     ...
;     u32x4 rv[4];
; #pragma unroll
;     for (int i = 0; i < 4; ++i) { const int idx = tid + 512 * i, s = idx >> 4, ch = (idx & 15) * 8; rv[i] = *(const u32x4*)(PROJ + (row0 + s) * NPROJ + C_VS + hh * 128 + ch); }
;     u32x2 uw[8];
; #pragma unroll
;     for (int dct = 0; dct < 8; ++dct) uw[dct] = *(const u32x2*)(PROJ + (row0 + 16 * w + (lane & 15)) * NPROJ + C_U + hh * 128 + 16 * dct + (lane >> 4) * 4);
;     const float bs = bsp[hh * 128 + 16 * w + (lane & 15)];
;     if (hh != hh_cached) {
;         const int t = tid >> 2, s0 = (tid & 3) * 32; const float* wp = wsp + ((size_t)hh * 128 + t) * 128 + s0;
; #pragma unroll
;         for (int q = 0; q < 4; ++q) { const f32x4 a = *(const f32x4*)(wp + 8 * q), b = *(const f32x4*)(wp + 8 * q + 4); const int s = s0 + 8 * q;
;             u32x4 o; o.x = pk2(s <= t ? a.x : 0.f, s + 1 <= t ? a.y : 0.f); o.y = pk2(s + 2 <= t ? a.z : 0.f, s + 3 <= t ? a.w : 0.f);
;             o.z = pk2(s + 4 <= t ? b.x : 0.f, s + 5 <= t ? b.y : 0.f); o.w = pk2(s + 6 <= t ? b.z : 0.f, s + 7 <= t ? b.w : 0.f);
;             *(LAS u32x4*)(Wm + t * LD2 + s) = o; }
.LBB0_236:
	s_ashr_i32 s58, s50, 6
	s_ashr_i32 s59, s58, 31
	s_lshl_b32 s6, s50, 5
	s_lshl_b64 s[78:79], s[58:59], 11
	s_and_b32 s6, s6, 0x780
	s_or_b32 s78, s78, s6
	v_or_b32_e32 v0, s78, v32
	v_mov_b64_e32 v[16:17], s[4:5]
	s_and_b32 s56, s50, 3
	v_mad_u64_u32 v[0:1], s[58:59], v0, s30, v[16:17]
	v_mad_i32_i24 v1, s79, v154, v1
	s_lshl_b32 s6, s56, 8
	v_or_b32_e32 v2, s78, v68
	v_lshl_add_u64 v[0:1], v[0:1], 0, s[6:7]
	v_lshlrev_b32_e32 v52, 1, v60
	v_mad_u64_u32 v[2:3], s[58:59], v2, s30, v[16:17]
	v_readfirstlane_b32 s55, v129
	v_lshl_add_u64 v[0:1], v[0:1], 0, v[52:53]
	v_mad_i32_i24 v3, s79, v154, v3
	v_or_b32_e32 v8, s78, v70
	v_add_co_u32_e32 v0, vcc, s3, v0
	v_lshl_add_u64 v[2:3], v[2:3], 0, s[6:7]
	v_mad_u64_u32 v[8:9], s[58:59], v8, s30, v[16:17]
	s_lshr_b32 s54, s55, 2
	s_lshl_b32 s35, s56, 7
	v_addc_co_u32_e32 v1, vcc, 0, v1, vcc
	v_lshl_add_u64 v[2:3], v[2:3], 0, v[52:53]
	v_mad_i32_i24 v9, s79, v154, v9
	v_lshl_add_u64 v[10:11], s[78:79], 0, v[72:73]
	s_and_b32 s54, s54, 0x3ffffff0
	v_add_co_u32_e32 v4, vcc, s3, v2
	v_lshl_add_u64 v[8:9], v[8:9], 0, s[6:7]
	v_mad_u64_u32 v[12:13], s[58:59], v10, s30, v[16:17]
	s_add_u32 s57, s78, s54
	v_addc_co_u32_e32 v5, vcc, 0, v3, vcc
	v_lshl_add_u64 v[8:9], v[8:9], 0, v[52:53]
	v_mad_i32_i24 v13, v11, s30, v13
	v_or_b32_e32 v18, s57, v64
	v_add_co_u32_e32 v8, vcc, s3, v8
	v_lshl_add_u64 v[10:11], v[12:13], 0, s[6:7]
	s_addc_u32 s60, s79, 0
	v_mad_u64_u32 v[16:17], s[58:59], v18, s30, v[16:17]
	v_addc_co_u32_e32 v9, vcc, 0, v9, vcc
	v_lshl_add_u64 v[10:11], v[10:11], 0, v[52:53]
	v_mad_i32_i24 v17, s60, v154, v17
	v_add_co_u32_e32 v12, vcc, s3, v10
	v_lshl_add_u64 v[16:17], v[16:17], 0, s[6:7]
	v_lshlrev_b32_e32 v102, 1, v66
	v_mov_b32_e32 v103, v53
	v_addc_co_u32_e32 v13, vcc, 0, v11, vcc
	v_lshl_add_u64 v[16:17], v[16:17], 0, v[102:103]
	global_load_dwordx4 v[0:3], v[0:1], off offset:32
	s_nop 0
	global_load_dwordx4 v[4:7], v[4:5], off offset:32
	s_nop 0
	global_load_dwordx4 v[8:11], v[8:9], off offset:32
	s_nop 0
	global_load_dwordx4 v[12:15], v[12:13], off offset:32
	s_nop 0
	v_lshrrev_b32_e32 v230, 4, v128
	v_and_b32_e32 v230, 1, v230
	v_mul_u32_u24_e32 v230, 24, v230
	v_mov_b32_e32 v231, 0
	v_lshl_add_u64 v[228:229], v[16:17], 0, v[230:231]
	global_load_dwordx4 v[240:243], v[228:229], off offset:3104
	global_load_dwordx4 v[244:247], v[228:229], off offset:3168
	global_load_dwordx4 v[248:251], v[228:229], off offset:3232
	global_load_dwordx4 v[252:255], v[228:229], off offset:3296
	s_add_i32 s6, s54, s35
	v_or_b32_e32 v52, s6, v64
	v_lshl_add_u64 v[16:17], v[52:53], 2, s[48:49]
	global_load_dword v79, v[16:17], off
	s_cmp_eq_u32 s56, s51
	s_cbranch_scc1 .LBB0_238
	s_lshl_b32 s6, s56, 14
	v_add_lshl_u32 v52, s6, v119, 2
	v_lshl_add_u64 v[16:17], v[74:75], 0, v[52:53]
	global_load_dwordx4 v[18:21], v[16:17], off offset:16
	global_load_dwordx4 v[22:25], v[16:17], off
	global_load_dwordx4 v[204:207], v[16:17], off offset:48
	global_load_dwordx4 v[208:211], v[16:17], off offset:32
	global_load_dwordx4 v[212:215], v[16:17], off offset:80
	global_load_dwordx4 v[216:219], v[16:17], off offset:64
	global_load_dwordx4 v[220:223], v[16:17], off offset:112
	global_load_dwordx4 v[224:227], v[16:17], off offset:96
	v_readlane_b32 s58, v237, 20
	v_readlane_b32 s59, v237, 21
	s_mov_b32 s51, s56
	s_waitcnt vmcnt(0)
	v_cndmask_b32_e64 v22, v22, 0, s[58:59]
	v_readlane_b32 s58, v237, 22
	v_readlane_b32 s59, v237, 23
	s_nop 1
	v_cndmask_b32_e64 v23, 0, v23, s[58:59]
	v_readlane_b32 s58, v237, 24
	v_readlane_b32 s59, v237, 25
	v_cvt_pk_bf16_f32 v22, v22, v23
	s_nop 1
	v_cndmask_b32_e64 v23, v24, 0, s[58:59]
	v_readlane_b32 s58, v237, 26
	v_readlane_b32 s59, v237, 27
	s_nop 1
	v_cndmask_b32_e64 v24, v25, 0, s[58:59]
	v_readlane_b32 s58, v237, 28
	v_readlane_b32 s59, v237, 29
	v_cvt_pk_bf16_f32 v23, v23, v24
	s_nop 1
	v_cndmask_b32_e64 v18, v18, 0, s[58:59]
	v_readlane_b32 s58, v237, 30
	v_readlane_b32 s59, v237, 31
	s_nop 1
	v_cndmask_b32_e64 v19, v19, 0, s[58:59]
	v_readlane_b32 s58, v237, 32
	v_readlane_b32 s59, v237, 33
	v_cvt_pk_bf16_f32 v24, v18, v19
	s_nop 1
	v_cndmask_b32_e64 v18, v20, 0, s[58:59]
	v_readlane_b32 s58, v237, 34
	v_readlane_b32 s59, v237, 35
	s_nop 1
	v_cndmask_b32_e64 v19, v21, 0, s[58:59]
	v_cvt_pk_bf16_f32 v25, v18, v19
	ds_write_b128 v120, v[22:25] offset:34816
	s_nop 0
	s_nop 0
	v_readlane_b32 s58, v237, 36
	v_readlane_b32 s59, v237, 37
	s_nop 0
	s_nop 0
	v_cndmask_b32_e64 v22, v208, 0, s[58:59]
	v_readlane_b32 s58, v237, 38
	v_readlane_b32 s59, v237, 39
	s_nop 1
	v_cndmask_b32_e64 v23, 0, v209, s[58:59]
	v_readlane_b32 s58, v237, 40
	v_readlane_b32 s59, v237, 41
	v_cvt_pk_bf16_f32 v22, v22, v23
	s_nop 1
	v_cndmask_b32_e64 v23, v210, 0, s[58:59]
	v_readlane_b32 s58, v237, 42
	v_readlane_b32 s59, v237, 43
	s_nop 1
	v_cndmask_b32_e64 v24, v211, 0, s[58:59]
	v_readlane_b32 s58, v237, 44
	v_readlane_b32 s59, v237, 45
	v_cvt_pk_bf16_f32 v23, v23, v24
	s_nop 1
	v_cndmask_b32_e64 v18, v204, 0, s[58:59]
	v_readlane_b32 s58, v237, 46
	v_readlane_b32 s59, v237, 47
	s_nop 1
	v_cndmask_b32_e64 v19, v205, 0, s[58:59]
	v_readlane_b32 s58, v237, 48
	v_readlane_b32 s59, v237, 49
	v_cvt_pk_bf16_f32 v24, v18, v19
	s_nop 1
	v_cndmask_b32_e64 v18, v206, 0, s[58:59]
	v_readlane_b32 s58, v237, 50
	v_readlane_b32 s59, v237, 51
	s_nop 1
	v_cndmask_b32_e64 v19, v207, 0, s[58:59]
	v_cvt_pk_bf16_f32 v25, v18, v19
	ds_write_b128 v120, v[22:25] offset:34832
	s_nop 0
	s_nop 0
	v_readlane_b32 s58, v237, 52
	v_readlane_b32 s59, v237, 53
	s_nop 0
	s_nop 0
	v_cndmask_b32_e64 v22, v216, 0, s[58:59]
	v_readlane_b32 s58, v237, 54
	v_readlane_b32 s59, v237, 55
	s_nop 1
	v_cndmask_b32_e64 v23, 0, v217, s[58:59]
; #define LAS __attribute__((address_space(3)))
; __device__ __forceinline__ unsigned pk2(float lo, float hi) { unsigned r; asm("v_cvt_pk_bf16_f32 %0, %1, %2" : "=v"(r) : "v"(lo), "v"(hi)); return r; }
; __device__ __forceinline__ void sgu_prompt_item(int item, const u16* PROJ, u16* MIXIN, const float* gln, const float* bln, const float* wsp, const float* bsp, LAS unsigned char* lds, int& hh_cached) {
;     ...
;         const int t = tid >> 2, s0 = (tid & 3) * 32; const float* wp = wsp + ((size_t)hh * 128 + t) * 128 + s0;
; #pragma unroll
;         for (int q = 0; q < 4; ++q) { const f32x4 a = *(const f32x4*)(wp + 8 * q), b = *(const f32x4*)(wp + 8 * q + 4); const int s = s0 + 8 * q;
;             u32x4 o; o.x = pk2(s <= t ? a.x : 0.f, s + 1 <= t ? a.y : 0.f); o.y = pk2(s + 2 <= t ? a.z : 0.f, s + 3 <= t ? a.w : 0.f);
;             o.z = pk2(s + 4 <= t ? b.x : 0.f, s + 5 <= t ? b.y : 0.f); o.w = pk2(s + 6 <= t ? b.z : 0.f, s + 7 <= t ? b.w : 0.f);
;             *(LAS u32x4*)(Wm + t * LD2 + s) = o; }
	v_readlane_b32 s58, v237, 56
	v_readlane_b32 s59, v237, 57
	v_cvt_pk_bf16_f32 v22, v22, v23
	s_nop 1
	v_cndmask_b32_e64 v23, v218, 0, s[58:59]
	v_readlane_b32 s58, v237, 58
	v_readlane_b32 s59, v237, 59
	s_nop 1
	v_cndmask_b32_e64 v24, v219, 0, s[58:59]
	v_readlane_b32 s58, v237, 60
	v_readlane_b32 s59, v237, 61
	v_cvt_pk_bf16_f32 v23, v23, v24
	s_nop 1
	v_cndmask_b32_e64 v18, v212, 0, s[58:59]
	v_readlane_b32 s58, v237, 62
	v_readlane_b32 s59, v237, 63
	s_nop 1
	v_cndmask_b32_e64 v19, v213, 0, s[58:59]
	v_readlane_b32 s58, v236, 0
	v_readlane_b32 s59, v236, 1
	v_cvt_pk_bf16_f32 v24, v18, v19
	s_nop 1
	v_cndmask_b32_e64 v18, v214, 0, s[58:59]
	v_readlane_b32 s58, v236, 2
	v_readlane_b32 s59, v236, 3
	s_nop 1
	v_cndmask_b32_e64 v19, v215, 0, s[58:59]
	v_cvt_pk_bf16_f32 v25, v18, v19
	ds_write_b128 v120, v[22:25] offset:34848
	s_nop 0
	s_nop 0
	v_readlane_b32 s58, v236, 4
	v_readlane_b32 s59, v236, 5
	s_nop 0
	v_cndmask_b32_e64 v18, v220, 0, s[68:69]
	s_nop 0
	v_cndmask_b32_e64 v16, v224, 0, s[58:59]
	v_readlane_b32 s58, v236, 6
	v_readlane_b32 s59, v236, 7
	v_cndmask_b32_e64 v19, v221, 0, s[70:71]
	v_cvt_pk_bf16_f32 v18, v18, v19
	v_cndmask_b32_e64 v19, v222, 0, s[72:73]
	v_cndmask_b32_e64 v17, 0, v225, s[58:59]
	v_readlane_b32 s58, v236, 8
	v_readlane_b32 s59, v236, 9
	v_cvt_pk_bf16_f32 v16, v16, v17
	v_cndmask_b32_e64 v22, v227, 0, s[66:67]
	v_cndmask_b32_e64 v20, v223, 0, s[74:75]
	v_cndmask_b32_e64 v17, v226, 0, s[58:59]
	v_cvt_pk_bf16_f32 v17, v17, v22
	v_cvt_pk_bf16_f32 v19, v19, v20
	ds_write_b128 v120, v[16:19] offset:34864
; #define LAS __attribute__((address_space(3)))
; __device__ __forceinline__ float bf2f(unsigned b) { return __uint_as_float(b << 16); }
; #define LBAR() do { asm volatile("s_waitcnt lgkmcnt(0)" ::: "memory"); __builtin_amdgcn_s_barrier(); asm volatile("" ::: "memory"); } while (0)
; __device__ __forceinline__ void sgu_prompt_item(int item, const u16* PROJ, u16* MIXIN, const float* gln, const float* bln, const float* wsp, const float* bsp, LAS unsigned char* lds, int& hh_cached) {
;     ...
;     for (int i = 0; i < 4; ++i) { const int idx = tid + 512 * i, s = idx >> 4, ch = (idx & 15) * 8; *(LAS u32x4*)(RAW + s * LD2 + ch) = rv[i]; }
;     LBAR();
;     { const int s = tid >> 2, qd = tid & 3; float s1 = 0.f, s2 = 0.f;
; #pragma unroll
;       for (int i = 0; i < 4; ++i) { const u32x4 r = *(const LAS u32x4*)(RAW + s * LD2 + qd * 32 + 8 * i);
;           const unsigned ww[4] = {r.x, r.y, r.z, r.w};
; #pragma unroll
;           for (int k = 0; k < 4; ++k) { const float a = bf2f(ww[k] & 0xffffu), b = bf2f(ww[k] >> 16); s1 += a + b; s2 += a * a + b * b; } }
;       s1 += __shfl_xor(s1, 1); s2 += __shfl_xor(s2, 1); s1 += __shfl_xor(s1, 2); s2 += __shfl_xor(s2, 2);
;       const float mu = s1 * (1.f / 128.f), var = fmaxf(s2 * (1.f / 128.f) - mu * mu, 0.f);
;       if (qd == 0) { STAT[2 * s] = mu; STAT[2 * s + 1] = rsqrtf(var + EPS); } }
.LBB0_238:
	s_waitcnt vmcnt(0)
	v_permlane16_swap_b32_e32 v240, v242
	v_permlane16_swap_b32_e32 v241, v243
	v_permlane16_swap_b32_e32 v244, v246
	v_permlane16_swap_b32_e32 v245, v247
	v_permlane16_swap_b32_e32 v248, v250
	v_permlane16_swap_b32_e32 v249, v251
	v_permlane16_swap_b32_e32 v252, v254
	v_permlane16_swap_b32_e32 v253, v255
	v_mov_b32_e32 v104, v240
	v_mov_b32_e32 v105, v241
	v_mov_b32_e32 v100, v242
	v_mov_b32_e32 v101, v243
	v_mov_b32_e32 v98, v244
	v_mov_b32_e32 v99, v245
	v_mov_b32_e32 v96, v246
	v_mov_b32_e32 v97, v247
	v_mov_b32_e32 v94, v248
	v_mov_b32_e32 v95, v249
	v_mov_b32_e32 v92, v250
	v_mov_b32_e32 v93, v251
	v_mov_b32_e32 v90, v252
	v_mov_b32_e32 v91, v253
	v_mov_b32_e32 v88, v254
	v_mov_b32_e32 v89, v255
	ds_write_b128 v145, v[0:3]
	ds_write_b128 v146, v[4:7]
	ds_write_b128 v145, v[8:11] offset:17408
	ds_write_b128 v147, v[12:15]
	s_waitcnt lgkmcnt(0)
	s_barrier
	ds_read_b128 v[0:3], v148
	ds_read_b128 v[4:7], v148 offset:16
	ds_read_b128 v[8:11], v148 offset:32
	ds_read_b128 v[12:15], v148 offset:48
	v_and_b32_e32 v81, 64, v153
	s_waitcnt lgkmcnt(3)
	v_and_b32_e32 v17, 0xffff0000, v0
	v_and_b32_e32 v19, 0xffff0000, v1
	v_lshlrev_b32_e32 v1, 16, v1
	v_lshlrev_b32_e32 v0, 16, v0
	s_waitcnt lgkmcnt(2)
	v_lshlrev_b32_e32 v157, 16, v6
	v_and_b32_e32 v159, 0xffff0000, v6
	v_mul_f32_e32 v160, v0, v0
	v_mov_b32_e32 v6, v1
	v_mov_b32_e32 v161, v1
	v_mul_f32_e32 v18, v17, v17
	v_mul_f32_e32 v52, v19, v19
	v_pk_add_f32 v[18:19], v[160:161], v[18:19]
	v_pk_mul_f32 v[160:161], v[0:1], v[6:7] op_sel:[1,0] op_sel_hi:[0,1]
	v_pk_add_f32 v[0:1], v[0:1], v[16:17] op_sel:[1,0] op_sel_hi:[0,1]
	v_lshlrev_b32_e32 v21, 16, v2
	v_and_b32_e32 v23, 0xffff0000, v2
	v_mov_b32_e32 v161, v1
	v_mul_f32_e32 v20, v21, v21
	v_mul_f32_e32 v22, v23, v23
	v_lshlrev_b32_e32 v25, 16, v3
	v_and_b32_e32 v3, 0xffff0000, v3
	v_pk_add_f32 v[0:1], v[160:161], v[52:53]
	v_mul_f32_e32 v24, v25, v25
	v_mul_f32_e32 v2, v3, v3
	v_lshlrev_b32_e32 v27, 16, v4
	v_and_b32_e32 v29, 0xffff0000, v4
	v_pk_add_f32 v[0:1], v[18:19], v[0:1]
	v_pk_add_f32 v[16:17], v[20:21], v[22:23]
	v_mul_f32_e32 v26, v27, v27
	v_mul_f32_e32 v28, v29, v29
	v_lshlrev_b32_e32 v31, 16, v5
	v_and_b32_e32 v5, 0xffff0000, v5
	v_pk_add_f32 v[0:1], v[16:17], v[0:1]
	v_pk_add_f32 v[2:3], v[24:25], v[2:3]
	v_mul_f32_e32 v30, v31, v31
	v_mul_f32_e32 v4, v5, v5
	v_pk_add_f32 v[0:1], v[2:3], v[0:1]
	v_pk_add_f32 v[2:3], v[26:27], v[28:29]
	v_mul_f32_e32 v156, v157, v157
	v_mul_f32_e32 v158, v159, v159
	v_pk_add_f32 v[0:1], v[2:3], v[0:1]
	v_pk_add_f32 v[2:3], v[30:31], v[4:5]
	v_and_b32_e32 v5, 0xffff0000, v7
	v_pk_add_f32 v[0:1], v[2:3], v[0:1]
	v_pk_add_f32 v[2:3], v[156:157], v[158:159]
	v_mul_f32_e32 v4, v5, v5
	v_pk_add_f32 v[0:1], v[2:3], v[0:1]
	v_lshlrev_b32_e32 v3, 16, v7
	v_mul_f32_e32 v2, v3, v3
	v_pk_add_f32 v[2:3], v[2:3], v[4:5]
	s_waitcnt lgkmcnt(1)
	v_lshlrev_b32_e32 v5, 16, v8
	v_and_b32_e32 v7, 0xffff0000, v8
	v_mul_f32_e32 v4, v5, v5
	v_mul_f32_e32 v6, v7, v7
	v_lshlrev_b32_e32 v17, 16, v9
	v_and_b32_e32 v9, 0xffff0000, v9
	v_mul_f32_e32 v16, v17, v17
	v_mul_f32_e32 v8, v9, v9
	v_lshlrev_b32_e32 v19, 16, v10
	v_and_b32_e32 v21, 0xffff0000, v10
	v_pk_add_f32 v[0:1], v[2:3], v[0:1]
	v_pk_add_f32 v[2:3], v[4:5], v[6:7]
	v_mul_f32_e32 v18, v19, v19
	v_mul_f32_e32 v20, v21, v21
	v_lshlrev_b32_e32 v23, 16, v11
	v_and_b32_e32 v11, 0xffff0000, v11
	v_pk_add_f32 v[0:1], v[2:3], v[0:1]
	v_pk_add_f32 v[2:3], v[16:17], v[8:9]
	v_mul_f32_e32 v22, v23, v23
	v_mul_f32_e32 v10, v11, v11
	s_waitcnt lgkmcnt(0)
	v_lshlrev_b32_e32 v25, 16, v12
	v_and_b32_e32 v27, 0xffff0000, v12
	v_pk_add_f32 v[0:1], v[2:3], v[0:1]
	v_pk_add_f32 v[2:3], v[18:19], v[20:21]
	v_mul_f32_e32 v24, v25, v25
	v_mul_f32_e32 v26, v27, v27
	v_lshlrev_b32_e32 v29, 16, v13
	v_and_b32_e32 v13, 0xffff0000, v13
	v_pk_add_f32 v[0:1], v[2:3], v[0:1]
	v_pk_add_f32 v[2:3], v[22:23], v[10:11]
	v_mul_f32_e32 v28, v29, v29
	v_mul_f32_e32 v12, v13, v13
	v_lshlrev_b32_e32 v31, 16, v14
	v_and_b32_e32 v157, 0xffff0000, v14
	v_pk_add_f32 v[0:1], v[2:3], v[0:1]
	v_pk_add_f32 v[2:3], v[24:25], v[26:27]
	v_mul_f32_e32 v30, v31, v31
	v_mul_f32_e32 v156, v157, v157
	v_lshlrev_b32_e32 v159, 16, v15
	v_and_b32_e32 v15, 0xffff0000, v15
	v_xor_b32_e32 v52, 1, v153
	v_add_u32_e32 v81, 64, v81
	v_pk_add_f32 v[0:1], v[2:3], v[0:1]
	v_pk_add_f32 v[2:3], v[28:29], v[12:13]
	v_mul_f32_e32 v158, v159, v159
	v_mul_f32_e32 v14, v15, v15
	v_cmp_lt_i32_e32 vcc, v52, v81
	v_pk_add_f32 v[0:1], v[2:3], v[0:1]
	v_pk_add_f32 v[2:3], v[30:31], v[156:157]
	v_cndmask_b32_e32 v52, v153, v52, vcc
	v_pk_add_f32 v[0:1], v[2:3], v[0:1]
	v_pk_add_f32 v[2:3], v[158:159], v[14:15]
	v_lshlrev_b32_e32 v52, 2, v52
	v_pk_add_f32 v[0:1], v[2:3], v[0:1]
	ds_bpermute_b32 v3, v52, v1
	ds_bpermute_b32 v2, v52, v0
	s_waitcnt lgkmcnt(0)
	v_pk_add_f32 v[0:1], v[0:1], v[2:3]
	v_xor_b32_e32 v2, 2, v153
	v_cmp_lt_i32_e32 vcc, v2, v81
	s_nop 1
	v_cndmask_b32_e32 v2, v153, v2, vcc
	v_lshlrev_b32_e32 v2, 2, v2
	ds_bpermute_b32 v3, v2, v1
	ds_bpermute_b32 v2, v2, v0
	s_and_saveexec_b64 s[80:81], s[76:77]
	s_cbranch_execz .LBB0_240
	s_waitcnt lgkmcnt(0)
	v_pk_add_f32 v[0:1], v[0:1], v[2:3]
	s_brev_b32 s6, 60
	v_pk_mul_f32 v[0:1], v[0:1], s[6:7] op_sel_hi:[1,0]
	s_nop 0
	v_fma_f32 v0, -v1, v1, v0
	v_max_f32_e32 v0, 0, v0
	v_add_f32_e32 v0, 0x358637bd, v0
	v_mul_f32_e32 v2, 0x4b800000, v0
	v_cmp_gt_f32_e32 vcc, s21, v0
	s_nop 1
	v_cndmask_b32_e32 v0, v0, v2, vcc
	v_rsq_f32_e32 v0, v0
	s_nop 0
	v_mul_f32_e32 v2, 0x45800000, v0
	v_cndmask_b32_e32 v3, v0, v2, vcc
	v_mov_b32_e32 v2, v1
	ds_write_b64 v149, v[2:3]
